# indexer score loop software-pipelined inside each wave: MFMAs of the next 16-key group issue between the VALU ops of the current one (two accumulator sets)
# speedup vs baseline: 1.0025x; 1.0012x over previous
; #define GAS __attribute__((address_space(1)))
; __device__ __forceinline__ f32x4 mfma16(bf16x8 a, bf16x8 b, f32x4 c) { return __builtin_amdgcn_mfma_f32_16x16x32_bf16(a, b, c, 0, 0, 0); }
; __device__ __forceinline__ void indexer_unit(const Args& a, LAS unsigned char* lds, LAS unsigned long long* maskl, int b, int qblk, int wave, int lane) {
;     ...
;     for (int kt = wave; kt < nkt; kt += 8) {
;         const int key = 16 * kt + fr;
;         const bf16x8 b0 = nb0, b1 = nb1;
;         { const int k2 = kt + 8 < nkt ? kt + 8 : kt; const GAS bf16* p = ikn + (rowb + 16 * k2 + fr) * 64 + 8 * fq; nb0 = *(const GAS bf16x8*)p; nb1 = *(const GAS bf16x8*)(p + 32); }
; #pragma unroll
;         for (int rt = 0; rt < 8; ++rt) {
;             f32x4 acc = {0.f, 0.f, 0.f, 0.f};
;             __builtin_amdgcn_s_setprio(1); acc = mfma16(af[rt][0], b0, acc); acc = mfma16(af[rt][1], b1, acc); __builtin_amdgcn_s_setprio(0);
;             float part = wv[rt][0] * fmaxf(acc[0], 0.f) + wv[rt][1] * fmaxf(acc[1], 0.f) + wv[rt][2] * fmaxf(acc[2], 0.f) + wv[rt][3] * fmaxf(acc[3], 0.f);
;             part += __shfl_xor(part, 16); part += 0.f;
;             if ((fq & 1) == 0) sc[(2 * rt + (fq >> 1)) * 2048 + key] = part;
;         }
.LBB0_1084:
.LBB0_1085:
	s_add_i32 s4, s10, 8
	s_cmp_gt_u32 s4, s9
	s_cselect_b32 s4, s10, s4
	v_lshl_add_u32 v74, s4, 4, v117
	v_mov_b32_e32 v75, v4
	v_lshlrev_b64 v[74:75], 7, v[74:75]
	v_lshl_add_u64 v[78:79], v[82:83], 0, v[74:75]
	global_load_dwordx4 v[74:77], v[78:79], off
	global_load_dwordx4 v[78:81], v[78:79], off offset:64
	v_mfma_f32_16x16x32_bf16 v[128:131], v[0:3], v[70:73], 0
	v_mfma_f32_16x16x32_bf16 v[132:135], v[14:17], v[70:73], 0
	v_mfma_f32_16x16x32_bf16 v[136:139], v[18:21], v[70:73], 0
	v_mfma_f32_16x16x32_bf16 v[140:143], v[30:33], v[70:73], 0
	v_mfma_f32_16x16x32_bf16 v[144:147], v[34:37], v[70:73], 0
	v_mfma_f32_16x16x32_bf16 v[148:151], v[42:45], v[70:73], 0
	v_mfma_f32_16x16x32_bf16 v[152:155], v[54:57], v[70:73], 0
	v_mfma_f32_16x16x32_bf16 v[156:159], v[46:49], v[70:73], 0
	v_mfma_f32_16x16x32_bf16 v[128:131], v[6:9], v[66:69], v[128:131]
	v_mfma_f32_16x16x32_bf16 v[132:135], v[10:13], v[66:69], v[132:135]
	v_mfma_f32_16x16x32_bf16 v[136:139], v[22:25], v[66:69], v[136:139]
	v_mfma_f32_16x16x32_bf16 v[140:143], v[26:29], v[66:69], v[140:143]
	v_mfma_f32_16x16x32_bf16 v[144:147], v[38:41], v[66:69], v[144:147]
	v_mfma_f32_16x16x32_bf16 v[148:151], v[50:53], v[66:69], v[148:151]
	v_mfma_f32_16x16x32_bf16 v[152:155], v[58:61], v[66:69], v[152:155]
	v_mfma_f32_16x16x32_bf16 v[156:159], v[62:65], v[66:69], v[156:159]
.Lsw_loopA:
	s_add_i32 s11, s10, 8
	s_cmp_gt_u32 s11, s9
	s_cbranch_scc1 .Lsw_lastA
	s_waitcnt vmcnt(0) lgkmcnt(0)
	v_mov_b64_e32 v[70:71], v[74:75]
	v_mov_b64_e32 v[72:73], v[76:77]
	v_mov_b64_e32 v[66:67], v[78:79]
	v_mov_b64_e32 v[68:69], v[80:81]
	s_mov_b32 s10, s11
	s_add_i32 s4, s10, 8
	s_cmp_gt_u32 s4, s9
	s_cselect_b32 s4, s10, s4
	v_lshl_add_u32 v74, s4, 4, v117
	v_mov_b32_e32 v75, v4
	v_lshlrev_b64 v[74:75], 7, v[74:75]
	v_lshl_add_u64 v[78:79], v[82:83], 0, v[74:75]
	global_load_dwordx4 v[74:77], v[78:79], off
	global_load_dwordx4 v[78:81], v[78:79], off offset:64
	v_mfma_f32_16x16x32_bf16 v[206:209], v[0:3], v[70:73], 0
	v_max_f32_e32 v160, 0, v128
	v_max_f32_e32 v168, 0, v129
	v_fma_f32 v168, v168, v86, 0
	v_max_f32_e32 v161, 0, v130
	v_fmac_f32_e32 v168, v160, v85
	v_mfma_f32_16x16x32_bf16 v[210:213], v[14:17], v[70:73], 0
	v_max_f32_e32 v160, 0, v131
	v_fmac_f32_e32 v168, v161, v87
	v_fmac_f32_e32 v168, v160, v88
	v_max_f32_e32 v160, 0, v132
	v_max_f32_e32 v169, 0, v133
	v_mfma_f32_16x16x32_bf16 v[214:217], v[18:21], v[70:73], 0
	v_fma_f32 v169, v169, v90, 0
	v_max_f32_e32 v161, 0, v134
	v_fmac_f32_e32 v169, v160, v89
	v_max_f32_e32 v160, 0, v135
	v_fmac_f32_e32 v169, v161, v91
	v_mfma_f32_16x16x32_bf16 v[218:221], v[30:33], v[70:73], 0
	v_fmac_f32_e32 v169, v160, v92
	v_max_f32_e32 v160, 0, v136
	v_max_f32_e32 v170, 0, v137
	v_fma_f32 v170, v170, v94, 0
	v_max_f32_e32 v161, 0, v138
	v_mfma_f32_16x16x32_bf16 v[228:231], v[34:37], v[70:73], 0
	v_fmac_f32_e32 v170, v160, v93
	v_max_f32_e32 v160, 0, v139
	v_fmac_f32_e32 v170, v161, v95
	v_fmac_f32_e32 v170, v160, v96
	v_max_f32_e32 v160, 0, v140
	v_mfma_f32_16x16x32_bf16 v[232:235], v[42:45], v[70:73], 0
	v_max_f32_e32 v171, 0, v141
	v_fma_f32 v171, v171, v98, 0
	v_max_f32_e32 v161, 0, v142
	v_fmac_f32_e32 v171, v160, v97
	v_max_f32_e32 v160, 0, v143
	v_mfma_f32_16x16x32_bf16 v[236:239], v[54:57], v[70:73], 0
	v_fmac_f32_e32 v171, v161, v99
	v_fmac_f32_e32 v171, v160, v100
	v_max_f32_e32 v160, 0, v144
	v_max_f32_e32 v172, 0, v145
	v_fma_f32 v172, v172, v102, 0
	v_mfma_f32_16x16x32_bf16 v[240:243], v[46:49], v[70:73], 0
	v_max_f32_e32 v161, 0, v146
	v_fmac_f32_e32 v172, v160, v101
	v_max_f32_e32 v160, 0, v147
	v_fmac_f32_e32 v172, v161, v103
	v_fmac_f32_e32 v172, v160, v104
	v_mfma_f32_16x16x32_bf16 v[206:209], v[6:9], v[66:69], v[206:209]
	v_max_f32_e32 v160, 0, v148
	v_max_f32_e32 v173, 0, v149
	v_fma_f32 v173, v173, v106, 0
	v_max_f32_e32 v161, 0, v150
	v_fmac_f32_e32 v173, v160, v105
	v_mfma_f32_16x16x32_bf16 v[210:213], v[10:13], v[66:69], v[210:213]
	v_max_f32_e32 v160, 0, v151
	v_fmac_f32_e32 v173, v161, v107
	v_fmac_f32_e32 v173, v160, v108
	v_max_f32_e32 v160, 0, v152
	v_max_f32_e32 v174, 0, v153
	v_mfma_f32_16x16x32_bf16 v[214:217], v[22:25], v[66:69], v[214:217]
	v_fma_f32 v174, v174, v110, 0
	v_max_f32_e32 v161, 0, v154
	v_fmac_f32_e32 v174, v160, v109
	v_max_f32_e32 v160, 0, v155
	v_fmac_f32_e32 v174, v161, v111
	v_mfma_f32_16x16x32_bf16 v[218:221], v[26:29], v[66:69], v[218:221]
	v_fmac_f32_e32 v174, v160, v112
	v_max_f32_e32 v160, 0, v156
	v_max_f32_e32 v175, 0, v157
	v_fma_f32 v175, v175, v114, 0
	v_max_f32_e32 v161, 0, v158
	v_mfma_f32_16x16x32_bf16 v[228:231], v[38:41], v[66:69], v[228:231]
	v_fmac_f32_e32 v175, v160, v113
	v_max_f32_e32 v160, 0, v159
	v_fmac_f32_e32 v175, v161, v115
	v_fmac_f32_e32 v175, v160, v116
	s_nop 0
	v_mfma_f32_16x16x32_bf16 v[232:235], v[50:53], v[66:69], v[232:235]
	v_permlane16_swap_b32_e32 v168, v172
	v_permlane16_swap_b32_e32 v169, v173
	v_permlane16_swap_b32_e32 v170, v174
	v_permlane16_swap_b32_e32 v171, v175
	v_add_f32_e32 v168, v168, v172
	v_mfma_f32_16x16x32_bf16 v[236:239], v[58:61], v[66:69], v[236:239]
	v_add_f32_e32 v169, v169, v173
	v_add_f32_e32 v170, v170, v174
	v_add_f32_e32 v171, v171, v175
	v_and_b32_e32 v160, 16, v252
	v_lshl_add_u32 v160, v160, 12, v119
	v_mfma_f32_16x16x32_bf16 v[240:243], v[62:65], v[66:69], v[240:243]
	ds_write_b32 v160, v168
	ds_write_b32 v160, v169 offset:16384
	ds_write_b32 v160, v170 offset:32768
	ds_write_b32 v160, v171 offset:49152
	v_add_u32_e32 v119, 0x200, v119
; #define GAS __attribute__((address_space(1)))
; __device__ __forceinline__ f32x4 mfma16(bf16x8 a, bf16x8 b, f32x4 c) { return __builtin_amdgcn_mfma_f32_16x16x32_bf16(a, b, c, 0, 0, 0); }
; __device__ __forceinline__ void indexer_unit(const Args& a, LAS unsigned char* lds, LAS unsigned long long* maskl, int b, int qblk, int wave, int lane) {
;     ...
;     for (int kt = wave; kt < nkt; kt += 8) {
;         const int key = 16 * kt + fr;
;         const bf16x8 b0 = nb0, b1 = nb1;
;         { const int k2 = kt + 8 < nkt ? kt + 8 : kt; const GAS bf16* p = ikn + (rowb + 16 * k2 + fr) * 64 + 8 * fq; nb0 = *(const GAS bf16x8*)p; nb1 = *(const GAS bf16x8*)(p + 32); }
; #pragma unroll
;         for (int rt = 0; rt < 8; ++rt) {
;             f32x4 acc = {0.f, 0.f, 0.f, 0.f};
;             __builtin_amdgcn_s_setprio(1); acc = mfma16(af[rt][0], b0, acc); acc = mfma16(af[rt][1], b1, acc); __builtin_amdgcn_s_setprio(0);
;             float part = wv[rt][0] * fmaxf(acc[0], 0.f) + wv[rt][1] * fmaxf(acc[1], 0.f) + wv[rt][2] * fmaxf(acc[2], 0.f) + wv[rt][3] * fmaxf(acc[3], 0.f);
;             part += __shfl_xor(part, 16); part += 0.f;
;             if ((fq & 1) == 0) sc[(2 * rt + (fq >> 1)) * 2048 + key] = part;
;         }
.Lsw_loopB:
	s_add_i32 s11, s10, 8
	s_cmp_gt_u32 s11, s9
	s_cbranch_scc1 .Lsw_lastB
	s_waitcnt vmcnt(0) lgkmcnt(0)
	v_mov_b64_e32 v[70:71], v[74:75]
	v_mov_b64_e32 v[72:73], v[76:77]
	v_mov_b64_e32 v[66:67], v[78:79]
	v_mov_b64_e32 v[68:69], v[80:81]
	s_mov_b32 s10, s11
	s_add_i32 s4, s10, 8
	s_cmp_gt_u32 s4, s9
	s_cselect_b32 s4, s10, s4
	v_lshl_add_u32 v74, s4, 4, v117
	v_mov_b32_e32 v75, v4
	v_lshlrev_b64 v[74:75], 7, v[74:75]
	v_lshl_add_u64 v[78:79], v[82:83], 0, v[74:75]
	global_load_dwordx4 v[74:77], v[78:79], off
	global_load_dwordx4 v[78:81], v[78:79], off offset:64
	v_mfma_f32_16x16x32_bf16 v[128:131], v[0:3], v[70:73], 0
	v_max_f32_e32 v160, 0, v206
	v_max_f32_e32 v168, 0, v207
	v_fma_f32 v168, v168, v86, 0
	v_max_f32_e32 v161, 0, v208
	v_fmac_f32_e32 v168, v160, v85
	v_mfma_f32_16x16x32_bf16 v[132:135], v[14:17], v[70:73], 0
	v_max_f32_e32 v160, 0, v209
	v_fmac_f32_e32 v168, v161, v87
	v_fmac_f32_e32 v168, v160, v88
	v_max_f32_e32 v160, 0, v210
	v_max_f32_e32 v169, 0, v211
	v_mfma_f32_16x16x32_bf16 v[136:139], v[18:21], v[70:73], 0
	v_fma_f32 v169, v169, v90, 0
	v_max_f32_e32 v161, 0, v212
	v_fmac_f32_e32 v169, v160, v89
	v_max_f32_e32 v160, 0, v213
	v_fmac_f32_e32 v169, v161, v91
	v_mfma_f32_16x16x32_bf16 v[140:143], v[30:33], v[70:73], 0
	v_fmac_f32_e32 v169, v160, v92
	v_max_f32_e32 v160, 0, v214
	v_max_f32_e32 v170, 0, v215
	v_fma_f32 v170, v170, v94, 0
	v_max_f32_e32 v161, 0, v216
	v_mfma_f32_16x16x32_bf16 v[144:147], v[34:37], v[70:73], 0
	v_fmac_f32_e32 v170, v160, v93
	v_max_f32_e32 v160, 0, v217
	v_fmac_f32_e32 v170, v161, v95
	v_fmac_f32_e32 v170, v160, v96
	v_max_f32_e32 v160, 0, v218
	v_mfma_f32_16x16x32_bf16 v[148:151], v[42:45], v[70:73], 0
	v_max_f32_e32 v171, 0, v219
	v_fma_f32 v171, v171, v98, 0
	v_max_f32_e32 v161, 0, v220
	v_fmac_f32_e32 v171, v160, v97
	v_max_f32_e32 v160, 0, v221
	v_mfma_f32_16x16x32_bf16 v[152:155], v[54:57], v[70:73], 0
	v_fmac_f32_e32 v171, v161, v99
	v_fmac_f32_e32 v171, v160, v100
	v_max_f32_e32 v160, 0, v228
	v_max_f32_e32 v172, 0, v229
	v_fma_f32 v172, v172, v102, 0
	v_mfma_f32_16x16x32_bf16 v[156:159], v[46:49], v[70:73], 0
	v_max_f32_e32 v161, 0, v230
	v_fmac_f32_e32 v172, v160, v101
	v_max_f32_e32 v160, 0, v231
	v_fmac_f32_e32 v172, v161, v103
	v_fmac_f32_e32 v172, v160, v104
	v_mfma_f32_16x16x32_bf16 v[128:131], v[6:9], v[66:69], v[128:131]
	v_max_f32_e32 v160, 0, v232
	v_max_f32_e32 v173, 0, v233
	v_fma_f32 v173, v173, v106, 0
	v_max_f32_e32 v161, 0, v234
	v_fmac_f32_e32 v173, v160, v105
	v_mfma_f32_16x16x32_bf16 v[132:135], v[10:13], v[66:69], v[132:135]
	v_max_f32_e32 v160, 0, v235
	v_fmac_f32_e32 v173, v161, v107
	v_fmac_f32_e32 v173, v160, v108
	v_max_f32_e32 v160, 0, v236
	v_max_f32_e32 v174, 0, v237
	v_mfma_f32_16x16x32_bf16 v[136:139], v[22:25], v[66:69], v[136:139]
	v_fma_f32 v174, v174, v110, 0
	v_max_f32_e32 v161, 0, v238
	v_fmac_f32_e32 v174, v160, v109
	v_max_f32_e32 v160, 0, v239
	v_fmac_f32_e32 v174, v161, v111
	v_mfma_f32_16x16x32_bf16 v[140:143], v[26:29], v[66:69], v[140:143]
	v_fmac_f32_e32 v174, v160, v112
	v_max_f32_e32 v160, 0, v240
	v_max_f32_e32 v175, 0, v241
	v_fma_f32 v175, v175, v114, 0
	v_max_f32_e32 v161, 0, v242
	v_mfma_f32_16x16x32_bf16 v[144:147], v[38:41], v[66:69], v[144:147]
	v_fmac_f32_e32 v175, v160, v113
	v_max_f32_e32 v160, 0, v243
	v_fmac_f32_e32 v175, v161, v115
	v_fmac_f32_e32 v175, v160, v116
	s_nop 0
	v_mfma_f32_16x16x32_bf16 v[148:151], v[50:53], v[66:69], v[148:151]
	v_permlane16_swap_b32_e32 v168, v172
	v_permlane16_swap_b32_e32 v169, v173
	v_permlane16_swap_b32_e32 v170, v174
	v_permlane16_swap_b32_e32 v171, v175
	v_add_f32_e32 v168, v168, v172
	v_mfma_f32_16x16x32_bf16 v[152:155], v[58:61], v[66:69], v[152:155]
	v_add_f32_e32 v169, v169, v173
	v_add_f32_e32 v170, v170, v174
	v_add_f32_e32 v171, v171, v175
	v_and_b32_e32 v160, 16, v252
	v_lshl_add_u32 v160, v160, 12, v119
	v_mfma_f32_16x16x32_bf16 v[156:159], v[62:65], v[66:69], v[156:159]
	ds_write_b32 v160, v168
	ds_write_b32 v160, v169 offset:16384
	ds_write_b32 v160, v170 offset:32768
	ds_write_b32 v160, v171 offset:49152
	v_add_u32_e32 v119, 0x200, v119
	s_branch .Lsw_loopA
; __device__ __forceinline__ f32x4 mfma16(bf16x8 a, bf16x8 b, f32x4 c) { return __builtin_amdgcn_mfma_f32_16x16x32_bf16(a, b, c, 0, 0, 0); }
; __device__ __forceinline__ void indexer_unit(const Args& a, LAS unsigned char* lds, LAS unsigned long long* maskl, int b, int qblk, int wave, int lane) {
;     ...
;         for (int rt = 0; rt < 8; ++rt) {
;             f32x4 acc = {0.f, 0.f, 0.f, 0.f};
;             __builtin_amdgcn_s_setprio(1); acc = mfma16(af[rt][0], b0, acc); acc = mfma16(af[rt][1], b1, acc); __builtin_amdgcn_s_setprio(0);
;             float part = wv[rt][0] * fmaxf(acc[0], 0.f) + wv[rt][1] * fmaxf(acc[1], 0.f) + wv[rt][2] * fmaxf(acc[2], 0.f) + wv[rt][3] * fmaxf(acc[3], 0.f);
;             part += __shfl_xor(part, 16); part += 0.f;
;             if ((fq & 1) == 0) sc[(2 * rt + (fq >> 1)) * 2048 + key] = part;
;         }
;     }
.Lsw_lastA:
	v_max_f32_e32 v160, 0, v128
	v_max_f32_e32 v168, 0, v129
	v_fma_f32 v168, v168, v86, 0
	v_max_f32_e32 v161, 0, v130
	v_fmac_f32_e32 v168, v160, v85
	v_max_f32_e32 v160, 0, v131
	v_fmac_f32_e32 v168, v161, v87
	v_fmac_f32_e32 v168, v160, v88
	v_max_f32_e32 v160, 0, v132
	v_max_f32_e32 v169, 0, v133
	v_fma_f32 v169, v169, v90, 0
	v_max_f32_e32 v161, 0, v134
	v_fmac_f32_e32 v169, v160, v89
	v_max_f32_e32 v160, 0, v135
	v_fmac_f32_e32 v169, v161, v91
	v_fmac_f32_e32 v169, v160, v92
	v_max_f32_e32 v160, 0, v136
	v_max_f32_e32 v170, 0, v137
	v_fma_f32 v170, v170, v94, 0
	v_max_f32_e32 v161, 0, v138
	v_fmac_f32_e32 v170, v160, v93
	v_max_f32_e32 v160, 0, v139
	v_fmac_f32_e32 v170, v161, v95
	v_fmac_f32_e32 v170, v160, v96
	v_max_f32_e32 v160, 0, v140
	v_max_f32_e32 v171, 0, v141
	v_fma_f32 v171, v171, v98, 0
	v_max_f32_e32 v161, 0, v142
	v_fmac_f32_e32 v171, v160, v97
	v_max_f32_e32 v160, 0, v143
	v_fmac_f32_e32 v171, v161, v99
	v_fmac_f32_e32 v171, v160, v100
	v_max_f32_e32 v160, 0, v144
	v_max_f32_e32 v172, 0, v145
	v_fma_f32 v172, v172, v102, 0
	v_max_f32_e32 v161, 0, v146
	v_fmac_f32_e32 v172, v160, v101
	v_max_f32_e32 v160, 0, v147
	v_fmac_f32_e32 v172, v161, v103
	v_fmac_f32_e32 v172, v160, v104
	v_max_f32_e32 v160, 0, v148
	v_max_f32_e32 v173, 0, v149
	v_fma_f32 v173, v173, v106, 0
	v_max_f32_e32 v161, 0, v150
	v_fmac_f32_e32 v173, v160, v105
	v_max_f32_e32 v160, 0, v151
	v_fmac_f32_e32 v173, v161, v107
	v_fmac_f32_e32 v173, v160, v108
	v_max_f32_e32 v160, 0, v152
	v_max_f32_e32 v174, 0, v153
	v_fma_f32 v174, v174, v110, 0
	v_max_f32_e32 v161, 0, v154
	v_fmac_f32_e32 v174, v160, v109
	v_max_f32_e32 v160, 0, v155
	v_fmac_f32_e32 v174, v161, v111
	v_fmac_f32_e32 v174, v160, v112
	v_max_f32_e32 v160, 0, v156
	v_max_f32_e32 v175, 0, v157
	v_fma_f32 v175, v175, v114, 0
	v_max_f32_e32 v161, 0, v158
	v_fmac_f32_e32 v175, v160, v113
	v_max_f32_e32 v160, 0, v159
	v_fmac_f32_e32 v175, v161, v115
	v_fmac_f32_e32 v175, v160, v116
	s_nop 0
	v_permlane16_swap_b32_e32 v168, v172
	v_permlane16_swap_b32_e32 v169, v173
	v_permlane16_swap_b32_e32 v170, v174
	v_permlane16_swap_b32_e32 v171, v175
	v_add_f32_e32 v168, v168, v172
	v_add_f32_e32 v169, v169, v173
	v_add_f32_e32 v170, v170, v174
	v_add_f32_e32 v171, v171, v175
	v_and_b32_e32 v160, 16, v252
	v_lshl_add_u32 v160, v160, 12, v119
	ds_write_b32 v160, v168
	ds_write_b32 v160, v169 offset:16384
	ds_write_b32 v160, v170 offset:32768
	ds_write_b32 v160, v171 offset:49152
	s_branch .Lsw_exit
.Lsw_lastB:
	v_max_f32_e32 v160, 0, v206
	v_max_f32_e32 v168, 0, v207
	v_fma_f32 v168, v168, v86, 0
	v_max_f32_e32 v161, 0, v208
	v_fmac_f32_e32 v168, v160, v85
	v_max_f32_e32 v160, 0, v209
	v_fmac_f32_e32 v168, v161, v87
	v_fmac_f32_e32 v168, v160, v88
	v_max_f32_e32 v160, 0, v210
	v_max_f32_e32 v169, 0, v211
	v_fma_f32 v169, v169, v90, 0
	v_max_f32_e32 v161, 0, v212
	v_fmac_f32_e32 v169, v160, v89
	v_max_f32_e32 v160, 0, v213
	v_fmac_f32_e32 v169, v161, v91
	v_fmac_f32_e32 v169, v160, v92
	v_max_f32_e32 v160, 0, v214
	v_max_f32_e32 v170, 0, v215
	v_fma_f32 v170, v170, v94, 0
	v_max_f32_e32 v161, 0, v216
	v_fmac_f32_e32 v170, v160, v93
	v_max_f32_e32 v160, 0, v217
	v_fmac_f32_e32 v170, v161, v95
	v_fmac_f32_e32 v170, v160, v96
	v_max_f32_e32 v160, 0, v218
	v_max_f32_e32 v171, 0, v219
	v_fma_f32 v171, v171, v98, 0
	v_max_f32_e32 v161, 0, v220
	v_fmac_f32_e32 v171, v160, v97
	v_max_f32_e32 v160, 0, v221
	v_fmac_f32_e32 v171, v161, v99
	v_fmac_f32_e32 v171, v160, v100
	v_max_f32_e32 v160, 0, v228
	v_max_f32_e32 v172, 0, v229
	v_fma_f32 v172, v172, v102, 0
	v_max_f32_e32 v161, 0, v230
	v_fmac_f32_e32 v172, v160, v101
	v_max_f32_e32 v160, 0, v231
	v_fmac_f32_e32 v172, v161, v103
	v_fmac_f32_e32 v172, v160, v104
	v_max_f32_e32 v160, 0, v232
	v_max_f32_e32 v173, 0, v233
	v_fma_f32 v173, v173, v106, 0
	v_max_f32_e32 v161, 0, v234
	v_fmac_f32_e32 v173, v160, v105
	v_max_f32_e32 v160, 0, v235
	v_fmac_f32_e32 v173, v161, v107
	v_fmac_f32_e32 v173, v160, v108
	v_max_f32_e32 v160, 0, v236
	v_max_f32_e32 v174, 0, v237
	v_fma_f32 v174, v174, v110, 0
	v_max_f32_e32 v161, 0, v238
	v_fmac_f32_e32 v174, v160, v109
	v_max_f32_e32 v160, 0, v239
	v_fmac_f32_e32 v174, v161, v111
	v_fmac_f32_e32 v174, v160, v112
	v_max_f32_e32 v160, 0, v240
	v_max_f32_e32 v175, 0, v241
	v_fma_f32 v175, v175, v114, 0
	v_max_f32_e32 v161, 0, v242
	v_fmac_f32_e32 v175, v160, v113
	v_max_f32_e32 v160, 0, v243
	v_fmac_f32_e32 v175, v161, v115
	v_fmac_f32_e32 v175, v160, v116
	s_nop 0
	v_permlane16_swap_b32_e32 v168, v172
	v_permlane16_swap_b32_e32 v169, v173
	v_permlane16_swap_b32_e32 v170, v174
	v_permlane16_swap_b32_e32 v171, v175
	v_add_f32_e32 v168, v168, v172
	v_add_f32_e32 v169, v169, v173
	v_add_f32_e32 v170, v170, v174
	v_add_f32_e32 v171, v171, v175
	v_and_b32_e32 v160, 16, v252
	v_lshl_add_u32 v160, v160, 12, v119
	ds_write_b32 v160, v168
	ds_write_b32 v160, v169 offset:16384
	ds_write_b32 v160, v170 offset:32768
	ds_write_b32 v160, v171 offset:49152
.Lsw_exit:
	s_waitcnt vmcnt(0) lgkmcnt(0)
	s_branch .LBB0_1101
